# v20 + P4a: 14 dead per-token v_readlane SGPR restores deleted (only s[52:53] of the restored block is used in the loop)
# baseline (speedup 1.0000x reference)
; __device__ __forceinline__ void p4_load(TokIn& t, const bf16_t* PROJ, const bf16_t* RAW, const int* pos, int m, int lane) {
;     const bf16_t* pr = PROJ + (size_t)m * PP; const bf16_t* rr = RAW + (size_t)m * UPN;
; #pragma unroll
;     for (int h = 0; h < NH; ++h) {
; #pragma unroll
;         for (int i = 0; i < 3; ++i) t.q[h][i] = rr[h * QKD + lane + 64 * i];
; #pragma unroll
;         for (int i = 0; i < 2; ++i) t.k[h][i] = rr[768 + h * 256 + lane + 64 * i];
;     }
;     t.kpe = pr[C_KPE + lane]; t.cq = *(const u32x2*)(pr + C_CQ + 4 * lane); t.ckv = *(const unsigned*)(pr + C_CKV + 2 * lane); t.pos = pos[m];
; }
.LBB0_381:
	s_add_i32 s18, s31, s86
	s_cmpk_gt_i32 s18, 0x3fff
	s_cselect_b64 s[20:21], -1, 0
	s_and_b64 vcc, exec, s[20:21]
	s_cbranch_vccnz .LBB0_383
	s_ashr_i32 s19, s18, 31
	v_mad_i64_i32 v[14:15], s[0:1], s18, v43, v[8:9]
	s_lshl_b64 s[0:1], s[18:19], 12
	s_add_u32 s0, s46, s0
	s_addc_u32 s1, s47, s1
	v_lshl_add_u64 v[68:69], v[0:1], 1, s[0:1]
	global_load_ushort v48, v[14:15], off nt
	global_load_ushort v49, v[14:15], off offset:128 nt
	global_load_ushort v50, v[14:15], off offset:256 nt
	global_load_ushort v51, v[14:15], off offset:384 nt
	global_load_ushort v52, v[14:15], off offset:512 nt
	global_load_ushort v53, v[14:15], off offset:640 nt
	global_load_ushort v54, v[14:15], off offset:768 nt
	global_load_ushort v55, v[14:15], off offset:896 nt
	global_load_ushort v56, v[14:15], off offset:1536 nt
	global_load_ushort v58, v[14:15], off offset:1664 nt
	global_load_ushort v59, v[14:15], off offset:2048 nt
	global_load_ushort v61, v[14:15], off offset:2176 nt
	global_load_ushort v57, v[14:15], off offset:1024 nt
	global_load_ushort v60, v[14:15], off offset:1152 nt
	global_load_ushort v81, v[14:15], off offset:1280 nt
	global_load_ushort v83, v[14:15], off offset:1408 nt
	v_lshl_add_u64 v[84:85], v[68:69], 0, v[6:7]
	v_lshl_add_u64 v[86:87], v[2:3], 1, s[0:1]
	global_load_ushort v63, v[14:15], off offset:2560 nt
	global_load_ushort v64, v[14:15], off offset:2688 nt
	global_load_ushort v65, v[14:15], off offset:3072 nt
	global_load_ushort v66, v[14:15], off offset:3200 nt
	global_load_ushort v67, v[68:69], off offset:768 nt
	s_nop 0
	global_load_dwordx2 v[14:15], v[84:85], off
	global_load_dword v62, v[86:87], off offset:512
	v_readlane_b32 s52, v255, 4
	v_readlane_b32 s53, v255, 5
	s_lshl_b64 s[0:1], s[18:19], 2
	s_mov_b64 s[40:41], s[52:53]
	s_add_u32 s0, s40, s0
	s_addc_u32 s1, s41, s1
	global_load_dword v68, v5, s[0:1]
	s_waitcnt vmcnt(8)
	v_perm_b32 v69, v81, v83, s2
